# NSA selected attention: K/V tiles staged once per workgroup in LDS by DMA (3-stage ring, one barrier per key-tile pair), waves read MFMA fragments from LDS instead of each streaming K/V through L1
# speedup vs baseline: 1.0203x; 1.0203x over previous
; #define TIDX get_tid_()
; DI float bf2f(bf16_t b) { return __uint_as_float(((unsigned)b) << 16); }
; DI int crow(int i, int h) { return (i & 3) + 8 * (i >> 2) + 4 * h; }
; DI void nsa_main_item(const Params& p, int b, int head, int qb, const unsigned char* blut, const float* tbl) {
;   const int lane = TIDX & 63, r = lane & 31, h = lane >> 5;
;   const int g = head / 3, bg = b * 2 + g;
;   const int t = qb * 32 + r;
;   const float* tblh = tbl + head * 32;
;   bf16x8 qf[4];
;   load_q(qf, (const bf16_t*)(p.ws + OFF_QN) + (size_t)(b * 4096 + t) * 384 + head * 64 + 8 * h);
;   const unsigned long long selm = ((const unsigned long long*)(p.ws + OFF_SELM))[(size_t)bg * 4096 + t];
;   const float* gates = (const float*)(p.ws + OFF_GATES) + (size_t)(b * 4096 + t) * 18 + head * 3;
;   const float g1 = gates[1];
;   f32x16 y0, y1;
;   {
;     const bf16_t* oc = (const bf16_t*)(p.ws + OFF_OC) + (size_t)(b * 4096 + t) * 384 + head * 64;
;     const bf16_t* yw = (const bf16_t*)(p.ws + OFF_Y) + (size_t)(b * 4096 + t) * 768 + head * 64;
; #pragma unroll
;     for (int i = 0; i < 16; ++i) { y0[i] = bf2f(oc[crow(i, h)]) + bf2f(yw[crow(i, h)]); y1[i] = bf2f(oc[32 + crow(i, h)]) + bf2f(yw[32 + crow(i, h)]); }
;   }
;     ...
;   for (;;) {
;     const int item = wave_fetch(ctr);
;     if (item >= 128 * 48) break;
;     const int qb = 127 - item / 48, sub = item % 48;
;     nsa_main_item(p, sub / 6, sub % 6, qb, blut, tbl);
.LfY_skip:
	s_or_b64 exec, exec, s[8:9]
	s_barrier
	ds_read_b32 v0, v0
	v_lshrrev_b32_e32 v1, 6, v129
	s_waitcnt lgkmcnt(0)
	v_add_u32_e32 v0, v0, v1
	s_movk_i32 s8, 0x300
	s_waitcnt lgkmcnt(0)
	v_cmp_gt_i32_e32 vcc, s8, v0
	s_mov_b64 s[8:9], -1
	s_and_saveexec_b64 s[14:15], vcc
	s_cbranch_execz .LBB0_702
	v_lshrrev_b32_e32 v1, 4, v0
	v_lshlrev_b32_e32 v1, 3, v1
	v_and_b32_e32 v2, 7, v0
	v_add_u32_e32 v1, v1, v2
	v_bfe_u32 v2, v0, 3, 1
	v_mul_u32_u24_e32 v2, 3, v2
	v_add_u32_e32 v2, v2, v1
	v_mul_u32_u24_e32 v0, 0x5556, v1
	v_lshrrev_b32_e32 v0, 16, v0
	v_mul_u32_u24_e32 v0, 45, v0
	v_add3_u32 v0, v0, v2, s101
	s_mov_b32 s8, 0xd5555555
	v_mul_hi_i32 v1, v0, s8
	v_lshrrev_b32_e32 v2, 31, v1
	v_ashrrev_i32_e32 v1, 3, v1
	s_movk_i32 s8, 0x7f
	v_add3_u32 v217, v1, v2, s8
	s_mov_b32 s8, 0x2aaaaaab
	v_mul_hi_i32 v1, v0, s8
	v_lshrrev_b32_e32 v2, 31, v1
	v_lshrrev_b32_e32 v1, 3, v1
	v_add_u32_e32 v1, v1, v2
	v_mul_lo_u32 v1, v1, 48
	v_sub_u32_e32 v0, v0, v1
	v_mul_lo_u16_e32 v1, 43, v0
	v_lshrrev_b16_e32 v2, 15, v1
	v_add_u16_sdwa v1, v1, v2 dst_sel:DWORD dst_unused:UNUSED_PAD src0_sel:BYTE_1 src1_sel:DWORD
	v_bfe_i32 v2, v1, 0, 8
	v_mul_lo_u16_e32 v1, 6, v1
	v_sub_u16_e32 v0, v0, v1
	v_bfe_i32 v28, v0, 0, 8
	v_mov_b32_e32 v0, v129
	v_lshlrev_b32_e32 v31, 5, v217
	v_and_b32_e32 v29, 31, v0
	v_bfe_u32 v30, v0, 5, 1
	v_mul_lo_u16_e32 v0, 0x56, v28
	v_lshrrev_b16_e32 v1, 15, v0
	v_add_u16_sdwa v0, v0, v1 dst_sel:DWORD dst_unused:UNUSED_PAD src0_sel:BYTE_1 src1_sel:DWORD
	v_readlane_b32 s8, v253, 13
	v_bfe_i32 v0, v0, 0, 8
	v_or_b32_e32 v10, v29, v31
	v_readlane_b32 s9, v253, 14
	v_lshl_add_u32 v8, v2, 1, v0
	v_lshl_add_u32 v22, v2, 12, v10
	v_mov_b64_e32 v[0:1], s[8:9]
	s_movk_i32 s23, 0x300
	v_mad_i64_i32 v[0:1], s[8:9], v22, s23, v[0:1]
	v_lshlrev_b32_e32 v2, 6, v28
	v_ashrrev_i32_e32 v3, 31, v2
	v_readlane_b32 s8, v253, 23
	v_lshlrev_b64 v[2:3], 1, v[2:3]
	v_readlane_b32 s9, v253, 24
	v_lshl_add_u64 v[4:5], v[0:1], 0, v[2:3]
	v_lshlrev_b32_e32 v130, 3, v30
	v_mov_b64_e32 v[0:1], s[8:9]
	v_mad_i64_i32 v[0:1], s[8:9], v22, s23, v[0:1]
	v_readlane_b32 s8, v253, 19
	v_readlane_b32 s9, v253, 20
	v_lshl_add_u64 v[0:1], v[0:1], 0, v[2:3]
	v_ashrrev_i32_e32 v9, 31, v8
	v_mov_b64_e32 v[6:7], s[8:9]
	s_movk_i32 s8, 0x600
	v_mad_i64_i32 v[6:7], s[8:9], v22, s8, v[6:7]
	v_lshl_add_u64 v[2:3], v[6:7], 0, v[2:3]
	v_lshl_add_u64 v[12:13], v[0:1], 0, v[130:131]
	v_readlane_b32 s8, v253, 25
	v_lshlrev_b32_e32 v0, 3, v29
	v_lshl_add_u64 v[132:133], v[2:3], 0, v[130:131]
	v_lshlrev_b64 v[14:15], 19, v[8:9]
	v_readlane_b32 s9, v253, 26
	v_lshl_or_b32 v130, v30, 8, v0
	v_lshlrev_b32_e32 v20, 1, v130
	v_lshl_add_u64 v[16:17], s[8:9], 0, v[14:15]
	v_mov_b32_e32 v21, v131
	v_lshl_add_u64 v[148:149], v[16:17], 0, v[20:21]
	global_load_dwordx4 v[0:3], v[148:149], off
	v_lshlrev_b32_e32 v6, 4, v30
	v_mov_b32_e32 v7, v131
	v_lshl_add_u64 v[4:5], v[4:5], 0, v[6:7]
	global_load_dwordx4 v[80:83], v[4:5], off
	v_mov_b64_e32 v[6:7], s[34:35]
	s_movk_i32 s8, 0x48
	v_mad_i64_i32 v[6:7], s[8:9], v22, s8, v[6:7]
	v_mul_i32_i24_e32 v22, 3, v28
	v_ashrrev_i32_e32 v23, 31, v22
	v_cmp_eq_u32_e32 vcc, 0, v217
	v_lshl_add_u64 v[6:7], v[22:23], 2, v[6:7]
	s_mov_b32 s8, 0x165c4000
	v_cndmask_b32_e64 v18, v197, 0, vcc
	v_add_co_u32_e32 v22, vcc, s8, v6
	v_readlane_b32 s8, v253, 21
	s_nop 0
	v_addc_co_u32_e32 v23, vcc, 0, v7, vcc
	global_load_dwordx4 v[84:87], v[4:5], off offset:32
	global_load_dwordx4 v[88:91], v[4:5], off offset:64
	global_load_dwordx4 v[92:95], v[4:5], off offset:96
	global_load_dwordx2 v[136:137], v[12:13], off offset:64
	global_load_dwordx2 v[144:145], v[12:13], off offset:80
	global_load_dwordx2 v[150:151], v[12:13], off offset:32
	global_load_dwordx2 v[160:161], v[12:13], off offset:48
	global_load_dwordx2 v[134:135], v[132:133], off
	global_load_dwordx2 v[142:143], v[132:133], off offset:16
	global_load_dwordx2 v[152:153], v[132:133], off offset:32
	global_load_dwordx2 v[162:163], v[132:133], off offset:48
	global_load_dwordx2 v[154:155], v[12:13], off offset:96
	global_load_dwordx2 v[164:165], v[12:13], off offset:112
	global_load_dwordx4 v[4:7], v[148:149], off offset:1024
	global_load_dwordx2 v[138:139], v[132:133], off offset:64
	global_load_dwordx2 v[146:147], v[132:133], off offset:80
	global_load_dwordx2 v[158:159], v[132:133], off offset:96
	global_load_dwordx2 v[166:167], v[132:133], off offset:112
	v_lshlrev_b64 v[8:9], 15, v[8:9]
	v_readlane_b32 s9, v253, 22
	v_mov_b32_e32 v11, v131
	v_mov_b32_e32 v19, v131
	v_lshl_add_u64 v[8:9], s[8:9], 0, v[8:9]
	v_lshl_add_u64 v[24:25], v[10:11], 3, v[8:9]
	v_lshl_add_u64 v[26:27], v[16:17], 0, v[18:19]
	global_load_dwordx4 v[8:11], v[148:149], off offset:2048
	global_load_dwordx2 v[168:169], v[24:25], off
	global_load_dword v218, v[22:23], off offset:4
	global_load_dwordx2 v[140:141], v[12:13], off
	global_load_dwordx2 v[156:157], v[12:13], off offset:16
	global_load_dwordx4 v[16:19], v[148:149], off offset:3072
	v_readlane_b32 s8, v253, 27
	v_readlane_b32 s9, v253, 28
	v_lshl_add_u64 v[12:13], v[26:27], 0, v[20:21]
	global_load_dwordx4 v[108:111], v[12:13], off offset:3072
	global_load_dwordx4 v[104:107], v[12:13], off offset:2048
	global_load_dwordx4 v[100:103], v[12:13], off offset:1024
	global_load_dwordx4 v[96:99], v[12:13], off
	v_lshl_add_u64 v[14:15], s[8:9], 0, v[14:15]
	v_lshl_add_u64 v[170:171], v[14:15], 0, v[130:131]
	global_load_dwordx2 v[114:115], v[170:171], off offset:3584
	global_load_dwordx2 v[112:113], v[170:171], off offset:3072
	global_load_dwordx2 v[118:119], v[170:171], off offset:2560
	global_load_dwordx2 v[116:117], v[170:171], off offset:2048
	global_load_dwordx2 v[122:123], v[170:171], off offset:1536
	global_load_dwordx2 v[120:121], v[170:171], off offset:1024
	global_load_dwordx2 v[126:127], v[170:171], off offset:512
	global_load_dwordx2 v[124:125], v[170:171], off
	s_mov_b32 s56, 0
	s_mov_b32 s57, s56
	s_mov_b32 s58, s56
	s_mov_b32 s59, s56
	s_mov_b32 s60, s56
	s_mov_b32 s61, s56
	s_mov_b32 s62, s56
	s_mov_b32 s63, s56
	s_mov_b32 s64, s56
	s_mov_b32 s65, s56
	s_mov_b32 s66, s56
	s_mov_b32 s67, s56
	s_mov_b32 s68, s56
	s_mov_b32 s69, s56
	s_waitcnt vmcnt(36)
; #define MFMA32(a, b, c) __builtin_amdgcn_mfma_f32_32x32x16_bf16((a), (b), (c), 0, 0, 0)
; template <class KP, class VP, class ACT, class FILL>
; DI void attn_loop(AttnSt& st, const bf16x8 (&qf)[4], int k0, int k1, size_t vstride, KP kp, VP vp, ACT act, FILL fill) {
;   KVT cur, nxt;
;   {
;     KVT t0; load_kv(t0, kp(k0), vp(k0), vstride);
; #pragma unroll
;     for (int i = 0; i < 8; ++i) cur.v[i] = t0.v[i];
; #pragma unroll
;     for (int i = 0; i < 4; ++i) cur.k[i] = t0.k[i];
;   }
;   f32x16 s_cur;
;   { const float z = 0.f;
; #pragma unroll
;     for (int i = 0; i < 16; ++i) s_cur[i] = z; }
; #pragma unroll
;   for (int ss = 0; ss < 4; ++ss) s_cur = MFMA32(cur.k[ss], qf[ss], s_cur);
;   {
;     const int kn = (k0 < k1) ? k0 + 1 : k1;
;     const bf16_t* krow = kp(kn);
; #pragma unroll
;     for (int ss = 0; ss < 4; ++ss) nxt.k[ss] = *(const bf16x8*)(krow + 512 * ss);
;   }
;   for (int kt = k0; kt <= k1; ++kt) {
;     const int kn = (kt < k1) ? kt + 1 : k1;
;     const int kn2 = (kt + 2 <= k1) ? kt + 2 : k1;
;     {
;       const bf16_t* v0 = vp(kn);
; #pragma unroll
;       for (int j = 0; j < 8; ++j) nxt.v[j] = *(const s16x4*)(v0 + 256 * j);
;     }
;     bf16x8 k2[4];
;     {
;       const bf16_t* krow = kp(kn2);
; #pragma unroll
;       for (int ss = 0; ss < 4; ++ss) k2[ss] = *(const bf16x8*)(krow + 512 * ss);
;     }
	v_mfma_f32_32x32x16_bf16 v[48:63], v[0:3], v[80:83], 0
	s_mov_b32 s70, s56
	s_mov_b32 s71, s56
	v_lshlrev_b32_e32 v20, 2, v30
	v_lshl_add_u32 v219, v28, 7, 0
	v_subrev_u32_e32 v220, 31, v31
	v_sub_u32_e32 v221, v29, v20
	v_mov_b32_e32 v222, 0
	s_waitcnt vmcnt(22)
	v_mfma_f32_32x32x16_bf16 v[48:63], v[4:7], v[84:87], v[48:63]
	v_mov_b32_e32 v223, 0xff800000
	s_waitcnt vmcnt(17)
	v_mfma_f32_32x32x16_bf16 v[48:63], v[8:11], v[88:91], v[48:63]
	v_mov_b64_e32 v[0:1], s[56:57]
	v_mov_b64_e32 v[14:15], s[70:71]
	v_mov_b64_e32 v[2:3], s[58:59]
	v_mov_b64_e32 v[4:5], s[60:61]
	v_mov_b64_e32 v[6:7], s[62:63]
	v_mov_b64_e32 v[8:9], s[64:65]
	v_mov_b64_e32 v[10:11], s[66:67]
	s_waitcnt vmcnt(12)
	v_mfma_f32_32x32x16_bf16 v[48:63], v[16:19], v[92:95], v[48:63]
	v_mov_b64_e32 v[12:13], s[68:69]
	v_mov_b64_e32 v[30:31], v[14:15]
	s_mov_b64 s[58:59], 0
	v_mov_b64_e32 v[28:29], v[12:13]
	v_mov_b64_e32 v[26:27], v[10:11]
	v_mov_b64_e32 v[24:25], v[8:9]
	v_mov_b64_e32 v[22:23], v[6:7]
	v_mov_b64_e32 v[20:21], v[4:5]
	v_mov_b64_e32 v[18:19], v[2:3]
	v_mov_b64_e32 v[16:17], v[0:1]
	s_waitcnt vmcnt(0)
	v_readfirstlane_b32 s60, v217
	v_lshrrev_b32_e32 v246, 6, v129
	v_and_b32_e32 v247, 63, v129
	v_lshlrev_b32_e32 v247, 3, v247
	v_readfirstlane_b32 s58, v246
	v_mov_b32_e32 v224, s60
	v_mov_b32_e32 v225, 0x1940
	v_lshl_add_u32 v234, v246, 2, v225
	ds_write_b32 v234, v224
	s_waitcnt lgkmcnt(0)
	s_barrier
	ds_read_b128 v[226:229], v225
	ds_read_b128 v[230:233], v225 offset:16
	s_waitcnt lgkmcnt(0)
	v_max3_u32 v226, v226, v227, v228
	v_max3_u32 v226, v226, v229, v230
	v_max3_u32 v226, v226, v231, v232
	v_max_u32_e32 v226, v226, v233
	s_nop 0
	v_readfirstlane_b32 s59, v226
	s_mov_b32 s56, 0
	s_mov_b32 s23, 0
	s_mov_b32 s100, 0x10000
	s_lshr_b32 s24, s59, 1
	s_min_u32 s24, s23, s24
	s_lshl_b32 s26, s24, 13
	s_lshl_b32 s24, s58, 10
	s_add_u32 s26, s26, s24
	s_mov_b32 s27, 0
	v_lshl_add_u64 v[248:249], v[148:149], 0, s[26:27]
	v_lshl_add_u64 v[250:251], v[170:171], 0, s[26:27]
	v_add_co_u32_e32 v250, vcc, v250, v247
	v_addc_co_u32_e32 v251, vcc, 0, v251, vcc
	s_add_u32 s24, s24, s100
	s_mov_b32 m0, s24
	s_nop 0
	global_load_lds_dwordx4 v[248:249], off
	s_add_u32 s24, s24, 0x2000
	s_mov_b32 m0, s24
	s_nop 0
	global_load_lds_dwordx4 v[250:251], off
	s_mov_b32 s23, 1
	s_mov_b32 s100, 0x14000
	s_lshr_b32 s24, s59, 1
	s_min_u32 s24, s23, s24
	s_lshl_b32 s26, s24, 13
	s_lshl_b32 s24, s58, 10
	s_add_u32 s26, s26, s24
	s_mov_b32 s27, 0
	v_lshl_add_u64 v[248:249], v[148:149], 0, s[26:27]
	v_lshl_add_u64 v[250:251], v[170:171], 0, s[26:27]
	v_add_co_u32_e32 v250, vcc, v250, v247
	v_addc_co_u32_e32 v251, vcc, 0, v251, vcc
	s_add_u32 s24, s24, s100
	s_mov_b32 m0, s24
	s_nop 0
	global_load_lds_dwordx4 v[248:249], off
	s_add_u32 s24, s24, 0x2000
	s_mov_b32 m0, s24
	s_nop 0
	global_load_lds_dwordx4 v[250:251], off
	s_mov_b32 s100, 0x10000
	v_lshrrev_b32_e32 v246, 6, v129
	v_mul_u32_u24_e32 v246, 6912, v246
	v_add_u32_e32 v242, 8192, v246
	v_and_b32_e32 v246, 63, v129
	v_add_u32_e32 v224, -64, v246
	v_mov_b32_e32 v224, 0
	v_mov_b32_e32 v225, v246
	v_add_u32_e32 v226, 64, v246
	v_add_u32_e32 v227, 128, v246
	v_add_u32_e32 v228, 192, v246
	v_add_u32_e32 v229, 256, v246
	v_add_u32_e32 v230, 320, v246
	v_add_u32_e32 v231, 384, v246
	v_add_u32_e32 v232, 448, v246
	ds_read_u8 v224, v224
	ds_read_u8 v225, v225
	ds_read_u8 v226, v226
	ds_read_u8 v227, v227
	ds_read_u8 v228, v228
	ds_read_u8 v229, v229
	ds_read_u8 v230, v230
	ds_read_u8 v231, v231
	ds_read_u8 v232, v232
	s_waitcnt lgkmcnt(8)
	v_lshl_add_u32 v224, v224, 2, v219
	s_waitcnt lgkmcnt(7)
	v_lshl_add_u32 v225, v225, 2, v219
	s_waitcnt lgkmcnt(6)
	v_lshl_add_u32 v226, v226, 2, v219
	s_waitcnt lgkmcnt(5)
	v_lshl_add_u32 v227, v227, 2, v219
	s_waitcnt lgkmcnt(4)
	v_lshl_add_u32 v228, v228, 2, v219
	s_waitcnt lgkmcnt(3)
	v_lshl_add_u32 v229, v229, 2, v219
	s_waitcnt lgkmcnt(2)
	v_lshl_add_u32 v230, v230, 2, v219
	s_waitcnt lgkmcnt(1)
	v_lshl_add_u32 v231, v231, 2, v219
	s_waitcnt lgkmcnt(0)
	v_lshl_add_u32 v232, v232, 2, v219
	ds_read_b32 v224, v224 offset:4096
	ds_read_b32 v225, v225 offset:4096
	ds_read_b32 v226, v226 offset:4096
	ds_read_b32 v227, v227 offset:4096
	ds_read_b32 v228, v228 offset:4096
	ds_read_b32 v229, v229 offset:4096
	ds_read_b32 v230, v230 offset:4096
	ds_read_b32 v231, v231 offset:4096
	ds_read_b32 v232, v232 offset:4096
	v_lshl_add_u32 v244, v246, 2, v242
	s_waitcnt lgkmcnt(8)
	ds_write_b32 v244, v224 offset:0
	s_waitcnt lgkmcnt(7)
	ds_write_b32 v244, v225 offset:256
	s_waitcnt lgkmcnt(6)
	ds_write_b32 v244, v226 offset:512
	s_waitcnt lgkmcnt(5)
	ds_write_b32 v244, v227 offset:768
	s_waitcnt lgkmcnt(4)
	ds_write_b32 v244, v228 offset:1024
	s_waitcnt lgkmcnt(3)
	ds_write_b32 v244, v229 offset:1280
	s_waitcnt lgkmcnt(2)
	ds_write_b32 v244, v230 offset:1536
	s_waitcnt lgkmcnt(1)
	ds_write_b32 v244, v231 offset:1792
	s_waitcnt lgkmcnt(0)
	ds_write_b32 v244, v232 offset:2048
	v_add_u32_e32 v224, 512, v246
	v_add_u32_e32 v225, 576, v246
	v_add_u32_e32 v226, 640, v246
	v_add_u32_e32 v227, 704, v246
	v_add_u32_e32 v228, 768, v246
	v_add_u32_e32 v229, 832, v246
	v_add_u32_e32 v230, 896, v246
	v_add_u32_e32 v231, 960, v246
	v_add_u32_e32 v232, 1024, v246
	ds_read_u8 v224, v224
	ds_read_u8 v225, v225
	ds_read_u8 v226, v226
	ds_read_u8 v227, v227
	ds_read_u8 v228, v228
	ds_read_u8 v229, v229
	ds_read_u8 v230, v230
	ds_read_u8 v231, v231
	ds_read_u8 v232, v232
	s_waitcnt lgkmcnt(8)
	v_lshl_add_u32 v224, v224, 2, v219
	s_waitcnt lgkmcnt(7)
	v_lshl_add_u32 v225, v225, 2, v219
	s_waitcnt lgkmcnt(6)
	v_lshl_add_u32 v226, v226, 2, v219
	s_waitcnt lgkmcnt(5)
	v_lshl_add_u32 v227, v227, 2, v219
	s_waitcnt lgkmcnt(4)
; #define MFMA32(a, b, c) __builtin_amdgcn_mfma_f32_32x32x16_bf16((a), (b), (c), 0, 0, 0)
; template <class KP, class VP, class ACT, class FILL>
; DI void attn_loop(AttnSt& st, const bf16x8 (&qf)[4], int k0, int k1, size_t vstride, KP kp, VP vp, ACT act, FILL fill) {
;     ...
;   for (int kt = k0; kt <= k1; ++kt) {
;     const int kn = (kt < k1) ? kt + 1 : k1;
;     const int kn2 = (kt + 2 <= k1) ? kt + 2 : k1;
;     {
;       const bf16_t* v0 = vp(kn);
; #pragma unroll
;       for (int j = 0; j < 8; ++j) nxt.v[j] = *(const s16x4*)(v0 + 256 * j);
;     }
;     bf16x8 k2[4];
;     {
;       const bf16_t* krow = kp(kn2);
; #pragma unroll
;       for (int ss = 0; ss < 4; ++ss) k2[ss] = *(const bf16x8*)(krow + 512 * ss);
;     }
;     f32x16 s_next;
; #pragma unroll
;     for (int i = 0; i < 16; ++i) s_next[i] = 0.f;
; #pragma unroll
;     for (int ss = 0; ss < 4; ++ss) s_next = MFMA32(nxt.k[ss], qf[ss], s_next);
; DI void nsa_main_item(const Params& p, int b, int head, int qb, const unsigned char* blut, const float* tbl) {
;     ...
;       [&](int kt) { return __ballot((selm >> (kt >> 1)) & 1ull) != 0ull; },
;       [&](int kt, const f32x16& s, float (&lg)[16]) {
;         const bool bs = (selm >> (kt >> 1)) & 1ull;
	v_lshl_add_u32 v228, v228, 2, v219
	s_waitcnt lgkmcnt(3)
	v_lshl_add_u32 v229, v229, 2, v219
	s_waitcnt lgkmcnt(2)
	v_lshl_add_u32 v230, v230, 2, v219
	s_waitcnt lgkmcnt(1)
	v_lshl_add_u32 v231, v231, 2, v219
	s_waitcnt lgkmcnt(0)
	v_lshl_add_u32 v232, v232, 2, v219
	ds_read_b32 v224, v224 offset:4096
	ds_read_b32 v225, v225 offset:4096
	ds_read_b32 v226, v226 offset:4096
	ds_read_b32 v227, v227 offset:4096
	ds_read_b32 v228, v228 offset:4096
	ds_read_b32 v229, v229 offset:4096
	ds_read_b32 v230, v230 offset:4096
	ds_read_b32 v231, v231 offset:4096
	ds_read_b32 v232, v232 offset:4096
	v_lshl_add_u32 v244, v246, 2, v242
	s_waitcnt lgkmcnt(8)
	ds_write_b32 v244, v224 offset:2304
	s_waitcnt lgkmcnt(7)
	ds_write_b32 v244, v225 offset:2560
	s_waitcnt lgkmcnt(6)
	ds_write_b32 v244, v226 offset:2816
	s_waitcnt lgkmcnt(5)
	ds_write_b32 v244, v227 offset:3072
	s_waitcnt lgkmcnt(4)
	ds_write_b32 v244, v228 offset:3328
	s_waitcnt lgkmcnt(3)
	ds_write_b32 v244, v229 offset:3584
	s_waitcnt lgkmcnt(2)
	ds_write_b32 v244, v230 offset:3840
	s_waitcnt lgkmcnt(1)
	ds_write_b32 v244, v231 offset:4096
	s_waitcnt lgkmcnt(0)
	ds_write_b32 v244, v232 offset:4352
	v_add_u32_e32 v224, 1088, v246
	v_add_u32_e32 v225, 1152, v246
	v_add_u32_e32 v226, 1216, v246
	v_add_u32_e32 v227, 1280, v246
	v_add_u32_e32 v228, 1344, v246
	v_add_u32_e32 v229, 1408, v246
	v_add_u32_e32 v230, 1472, v246
	v_add_u32_e32 v231, 1536, v246
	v_add_u32_e32 v232, 1600, v246
	ds_read_u8 v224, v224
	ds_read_u8 v225, v225
	ds_read_u8 v226, v226
	ds_read_u8 v227, v227
	ds_read_u8 v228, v228
	ds_read_u8 v229, v229
	ds_read_u8 v230, v230
	ds_read_u8 v231, v231
	ds_read_u8 v232, v232
	s_waitcnt lgkmcnt(8)
	v_lshl_add_u32 v224, v224, 2, v219
	s_waitcnt lgkmcnt(7)
	v_lshl_add_u32 v225, v225, 2, v219
	s_waitcnt lgkmcnt(6)
	v_lshl_add_u32 v226, v226, 2, v219
	s_waitcnt lgkmcnt(5)
	v_lshl_add_u32 v227, v227, 2, v219
	s_waitcnt lgkmcnt(4)
	v_lshl_add_u32 v228, v228, 2, v219
	s_waitcnt lgkmcnt(3)
	v_lshl_add_u32 v229, v229, 2, v219
	s_waitcnt lgkmcnt(2)
	v_lshl_add_u32 v230, v230, 2, v219
	s_waitcnt lgkmcnt(1)
	v_lshl_add_u32 v231, v231, 2, v219
	s_waitcnt lgkmcnt(0)
	v_lshl_add_u32 v232, v232, 2, v219
	ds_read_b32 v224, v224 offset:4096
	ds_read_b32 v225, v225 offset:4096
	ds_read_b32 v226, v226 offset:4096
	ds_read_b32 v227, v227 offset:4096
	ds_read_b32 v228, v228 offset:4096
	ds_read_b32 v229, v229 offset:4096
	ds_read_b32 v230, v230 offset:4096
	ds_read_b32 v231, v231 offset:4096
	ds_read_b32 v232, v232 offset:4096
	v_lshl_add_u32 v244, v246, 2, v242
	s_waitcnt lgkmcnt(8)
	ds_write_b32 v244, v224 offset:4608
	s_waitcnt lgkmcnt(7)
	ds_write_b32 v244, v225 offset:4864
	s_waitcnt lgkmcnt(6)
	ds_write_b32 v244, v226 offset:5120
	s_waitcnt lgkmcnt(5)
	ds_write_b32 v244, v227 offset:5376
	s_waitcnt lgkmcnt(4)
	ds_write_b32 v244, v228 offset:5632
	s_waitcnt lgkmcnt(3)
	ds_write_b32 v244, v229 offset:5888
	s_waitcnt lgkmcnt(2)
	ds_write_b32 v244, v230 offset:6144
	s_waitcnt lgkmcnt(1)
	ds_write_b32 v244, v231 offset:6400
	s_waitcnt lgkmcnt(0)
	ds_write_b32 v244, v232 offset:6656
	ds_read_b32 v240, v219 offset:4220
	v_add_u32_e32 v242, 148, v242
	v_mov_b32_e32 v243, 0x7f800000
	s_waitcnt lgkmcnt(0)
.Lasel_loop:
	s_waitcnt vmcnt(2)
	s_barrier
	s_lshr_b32 s23, s56, 1
	s_add_u32 s23, s23, 2
	s_sub_u32 s61, s100, 0x4000
	s_cmp_lt_u32 s61, 0x10000
	s_cselect_b32 s61, 0x18000, s61
	s_lshr_b32 s24, s59, 1
	s_min_u32 s24, s23, s24
	s_lshl_b32 s26, s24, 13
	s_lshl_b32 s24, s58, 10
	s_add_u32 s26, s26, s24
	s_mov_b32 s27, 0
	v_lshl_add_u64 v[248:249], v[148:149], 0, s[26:27]
	v_lshl_add_u64 v[250:251], v[170:171], 0, s[26:27]
	v_add_co_u32_e32 v250, vcc, v250, v247
	v_addc_co_u32_e32 v251, vcc, 0, v251, vcc
	s_add_u32 s24, s24, s61
	s_mov_b32 m0, s24
	s_nop 0
	global_load_lds_dwordx4 v[248:249], off
	s_add_u32 s24, s24, 0x2000
	s_mov_b32 m0, s24
	s_nop 0
	global_load_lds_dwordx4 v[250:251], off
	s_cmp_le_u32 s56, s60
	s_cbranch_scc0 .Lasel_skip
	v_lshl_add_u32 v248, v247, 1, s100
	ds_read_b128 v[96:99], v248 offset:0
	ds_read_b128 v[100:103], v248 offset:1024
	ds_read_b128 v[104:107], v248 offset:2048
	ds_read_b128 v[108:111], v248 offset:3072
	ds_read_b128 v[112:115], v248 offset:4096
	ds_read_b128 v[116:119], v248 offset:5120
	ds_read_b128 v[120:123], v248 offset:6144
	ds_read_b128 v[124:127], v248 offset:7168
	s_sub_i32 s61, s60, s56
	s_lshr_b32 s23, s56, 1
	v_lshrrev_b64 v[248:249], s23, v[168:169]
	v_and_b32_e32 v248, 1, v248
	v_cmp_eq_u32_e64 s[62:63], 1, v248
	s_waitcnt lgkmcnt(0)
	v_mfma_f32_32x32x16_bf16 v[32:47], v[96:99], v[80:83], 0
	v_mfma_f32_32x32x16_bf16 v[48:63], v[112:115], v[80:83], 0
	v_mfma_f32_32x32x16_bf16 v[32:47], v[100:103], v[84:87], v[32:47]
	v_mfma_f32_32x32x16_bf16 v[48:63], v[116:119], v[84:87], v[48:63]
	v_mfma_f32_32x32x16_bf16 v[32:47], v[104:107], v[88:91], v[32:47]
	v_mfma_f32_32x32x16_bf16 v[48:63], v[120:123], v[88:91], v[48:63]
	v_mfma_f32_32x32x16_bf16 v[32:47], v[108:111], v[92:95], v[32:47]
	v_mfma_f32_32x32x16_bf16 v[48:63], v[124:127], v[92:95], v[48:63]
	v_add_u32_e32 v250, s100, v247
	ds_read_b64 v[64:65], v250 offset:8192
	ds_read_b64 v[66:67], v250 offset:8704
	ds_read_b64 v[68:69], v250 offset:9216
	ds_read_b64 v[70:71], v250 offset:9728
	ds_read_b64 v[72:73], v250 offset:10240
	ds_read_b64 v[74:75], v250 offset:10752
	ds_read_b64 v[76:77], v250 offset:11264
	ds_read_b64 v[78:79], v250 offset:11776
	ds_read_b64 v[172:173], v250 offset:12288
	ds_read_b64 v[174:175], v250 offset:12800
	ds_read_b64 v[176:177], v250 offset:13312
	ds_read_b64 v[178:179], v250 offset:13824
	ds_read_b64 v[180:181], v250 offset:14336
	ds_read_b64 v[182:183], v250 offset:14848
	ds_read_b64 v[184:185], v250 offset:15360
	ds_read_b64 v[186:187], v250 offset:15872
	s_cmp_ge_i32 s61, 50
	s_cbranch_scc1 .Lasel_far
; #define NEGINF (-__builtin_inff())
; DI int crow(int i, int h) { return (i & 3) + 8 * (i >> 2) + 4 * h; }
; DI void nsa_main_item(const Params& p, int b, int head, int qb, const unsigned char* blut, const float* tbl) {
;     ...
;         } else {
;           int dist[16]; float bv[16];
; #pragma unroll
;           for (int i = 0; i < 16; ++i) dist[i] = t - (kt * 32 + crow(i, h));
;           bias16(blut, tblh, dist, bv);
; #pragma unroll
;           for (int i = 0; i < 16; ++i) lg[i] = (bs && dist[i] >= 0) ? s[i] + bv[i] : NEGINF;
;         }
	s_lshl_b32 s23, s61, 5
	v_add_u32_e32 v241, s23, v221
	v_lshl_add_u32 v244, v241, 2, v242
	v_subrev_u32_e32 v245, 128, v244
	ds_read_b32 v224, v244 offset:108
	ds_read_b32 v225, v244 offset:104
	ds_read_b32 v226, v244 offset:100
	ds_read_b32 v227, v244 offset:96
	ds_read_b32 v228, v244 offset:76
	ds_read_b32 v229, v244 offset:72
	ds_read_b32 v230, v244 offset:68
	ds_read_b32 v231, v244 offset:64
	ds_read_b32 v232, v244 offset:44
	ds_read_b32 v233, v244 offset:40
	ds_read_b32 v234, v244 offset:36
	ds_read_b32 v235, v244 offset:32
	ds_read_b32 v236, v244 offset:12
	ds_read_b32 v237, v244 offset:8
	ds_read_b32 v238, v244 offset:4
	ds_read_b32 v239, v244 offset:0
	s_waitcnt lgkmcnt(8)
	v_add_f32_e32 v32, v32, v224
	v_add_f32_e32 v33, v33, v225
	v_add_f32_e32 v34, v34, v226
	v_add_f32_e32 v35, v35, v227
	v_add_f32_e32 v36, v36, v228
	v_add_f32_e32 v37, v37, v229
	v_add_f32_e32 v38, v38, v230
	v_add_f32_e32 v39, v39, v231
	s_waitcnt lgkmcnt(0)
	v_add_f32_e32 v40, v40, v232
	v_add_f32_e32 v41, v41, v233
	v_add_f32_e32 v42, v42, v234
	v_add_f32_e32 v43, v43, v235
	v_add_f32_e32 v44, v44, v236
	v_add_f32_e32 v45, v45, v237
	v_add_f32_e32 v46, v46, v238
	v_add_f32_e32 v47, v47, v239
	ds_read_b32 v224, v245 offset:108
	ds_read_b32 v225, v245 offset:104
	ds_read_b32 v226, v245 offset:100
	ds_read_b32 v227, v245 offset:96
	ds_read_b32 v228, v245 offset:76
	ds_read_b32 v229, v245 offset:72
	ds_read_b32 v230, v245 offset:68
	ds_read_b32 v231, v245 offset:64
	ds_read_b32 v232, v245 offset:44
	ds_read_b32 v233, v245 offset:40
	ds_read_b32 v234, v245 offset:36
	ds_read_b32 v235, v245 offset:32
	ds_read_b32 v236, v245 offset:12
	ds_read_b32 v237, v245 offset:8
	ds_read_b32 v238, v245 offset:4
	ds_read_b32 v239, v245 offset:0
	s_waitcnt lgkmcnt(8)
	v_add_f32_e32 v48, v48, v224
	v_add_f32_e32 v49, v49, v225
	v_add_f32_e32 v50, v50, v226
	v_add_f32_e32 v51, v51, v227
	v_add_f32_e32 v52, v52, v228
	v_add_f32_e32 v53, v53, v229
	v_add_f32_e32 v54, v54, v230
	v_add_f32_e32 v55, v55, v231
	s_waitcnt lgkmcnt(0)
	v_add_f32_e32 v56, v56, v232
	v_add_f32_e32 v57, v57, v233
	v_add_f32_e32 v58, v58, v234
	v_add_f32_e32 v59, v59, v235
	v_add_f32_e32 v60, v60, v236
	v_add_f32_e32 v61, v61, v237
	v_add_f32_e32 v62, v62, v238
	v_add_f32_e32 v63, v63, v239
	s_cmp_ge_i32 s61, 2
	s_cbranch_scc1 .Lasel_softmax
	v_subrev_u32_e32 v246, 32, v241
	v_cmp_le_i32_e32 vcc, 0, v241
	s_nop 1
	v_cndmask_b32_e32 v32, v199, v32, vcc
	v_cmp_le_i32_e32 vcc, 1, v241
	s_nop 1
	v_cndmask_b32_e32 v33, v199, v33, vcc
	v_cmp_le_i32_e32 vcc, 2, v241
	s_nop 1
	v_cndmask_b32_e32 v34, v199, v34, vcc
	v_cmp_le_i32_e32 vcc, 3, v241
	s_nop 1
	v_cndmask_b32_e32 v35, v199, v35, vcc
	v_cmp_le_i32_e32 vcc, 8, v241
	s_nop 1
	v_cndmask_b32_e32 v36, v199, v36, vcc
	v_cmp_le_i32_e32 vcc, 9, v241
	s_nop 1
	v_cndmask_b32_e32 v37, v199, v37, vcc
	v_cmp_le_i32_e32 vcc, 10, v241
	s_nop 1
	v_cndmask_b32_e32 v38, v199, v38, vcc
	v_cmp_le_i32_e32 vcc, 11, v241
	s_nop 1
	v_cndmask_b32_e32 v39, v199, v39, vcc
	v_cmp_le_i32_e32 vcc, 16, v241
	s_nop 1
	v_cndmask_b32_e32 v40, v199, v40, vcc
	v_cmp_le_i32_e32 vcc, 17, v241
	s_nop 1
	v_cndmask_b32_e32 v41, v199, v41, vcc
	v_cmp_le_i32_e32 vcc, 18, v241
	s_nop 1
	v_cndmask_b32_e32 v42, v199, v42, vcc
	v_cmp_le_i32_e32 vcc, 19, v241
	s_nop 1
	v_cndmask_b32_e32 v43, v199, v43, vcc
	v_cmp_le_i32_e32 vcc, 24, v241
	s_nop 1
	v_cndmask_b32_e32 v44, v199, v44, vcc
	v_cmp_le_i32_e32 vcc, 25, v241
	s_nop 1
	v_cndmask_b32_e32 v45, v199, v45, vcc
	v_cmp_le_i32_e32 vcc, 26, v241
	s_nop 1
	v_cndmask_b32_e32 v46, v199, v46, vcc
	v_cmp_le_i32_e32 vcc, 27, v241
	s_nop 1
	v_cndmask_b32_e32 v47, v199, v47, vcc
	v_cmp_le_i32_e32 vcc, 0, v246
	s_nop 1
	v_cndmask_b32_e32 v48, v199, v48, vcc
	v_cmp_le_i32_e32 vcc, 1, v246
	s_nop 1
	v_cndmask_b32_e32 v49, v199, v49, vcc
	v_cmp_le_i32_e32 vcc, 2, v246
	s_nop 1
	v_cndmask_b32_e32 v50, v199, v50, vcc
	v_cmp_le_i32_e32 vcc, 3, v246
	s_nop 1
	v_cndmask_b32_e32 v51, v199, v51, vcc
	v_cmp_le_i32_e32 vcc, 8, v246
	s_nop 1
	v_cndmask_b32_e32 v52, v199, v52, vcc
	v_cmp_le_i32_e32 vcc, 9, v246
	s_nop 1
	v_cndmask_b32_e32 v53, v199, v53, vcc
	v_cmp_le_i32_e32 vcc, 10, v246
	s_nop 1
	v_cndmask_b32_e32 v54, v199, v54, vcc
	v_cmp_le_i32_e32 vcc, 11, v246
	s_nop 1
	v_cndmask_b32_e32 v55, v199, v55, vcc
	v_cmp_le_i32_e32 vcc, 16, v246
	s_nop 1
	v_cndmask_b32_e32 v56, v199, v56, vcc
	v_cmp_le_i32_e32 vcc, 17, v246
	s_nop 1
	v_cndmask_b32_e32 v57, v199, v57, vcc
	v_cmp_le_i32_e32 vcc, 18, v246
	s_nop 1
	v_cndmask_b32_e32 v58, v199, v58, vcc
	v_cmp_le_i32_e32 vcc, 19, v246
	s_nop 1
	v_cndmask_b32_e32 v59, v199, v59, vcc
	v_cmp_le_i32_e32 vcc, 24, v246
	s_nop 1
	v_cndmask_b32_e32 v60, v199, v60, vcc
	v_cmp_le_i32_e32 vcc, 25, v246
	s_nop 1
	v_cndmask_b32_e32 v61, v199, v61, vcc
	v_cmp_le_i32_e32 vcc, 26, v246
	s_nop 1
	v_cndmask_b32_e32 v62, v199, v62, vcc
	v_cmp_le_i32_e32 vcc, 27, v246
	s_nop 1
	v_cndmask_b32_e32 v63, v199, v63, vcc
	s_branch .Lasel_softmax

; #define MFMA32(a, b, c) __builtin_amdgcn_mfma_f32_32x32x16_bf16((a), (b), (c), 0, 0, 0)
; DI unsigned pack2(float a, float b) { unsigned r; asm("v_cvt_pk_bf16_f32 %0, %1, %2" : "=v"(r) : "v"(a), "v"(b)); return r; }
; DI void softmax_step_r(AttnSt& st, const float (&lg)[16], const KVT& t) {
;     ...
;   for (int s2 = 0; s2 < 2; ++s2) {
;     u32x4 pk; pk.x = pack2(pr[8 * s2], pr[8 * s2 + 1]); pk.y = pack2(pr[8 * s2 + 2], pr[8 * s2 + 3]); pk.z = pack2(pr[8 * s2 + 4], pr[8 * s2 + 5]); pk.w = pack2(pr[8 * s2 + 6], pr[8 * s2 + 7]);
;     const bf16x8 pb = __builtin_bit_cast(bf16x8, pk);
;     const bf16x8 va0 = __builtin_shufflevector(t.v[s2 * 4 + 0], t.v[s2 * 4 + 1], 0, 1, 2, 3, 4, 5, 6, 7);
;     st.o0 = MFMA32(va0, pb, st.o0);
;     const bf16x8 va1 = __builtin_shufflevector(t.v[s2 * 4 + 2], t.v[s2 * 4 + 3], 0, 1, 2, 3, 4, 5, 6, 7);
;     st.o1 = MFMA32(va1, pb, st.o1);
;   }
; template <class KP, class VP, class ACT, class FILL>
; DI void attn_loop(AttnSt& st, const bf16x8 (&qf)[4], int k0, int k1, size_t vstride, KP kp, VP vp, ACT act, FILL fill) {
;     ...
;     s_cur = s_next;
; #pragma unroll
;     for (int i = 0; i < 8; ++i) cur.v[i] = nxt.v[i];
; #pragma unroll
;     for (int ss = 0; ss < 4; ++ss) nxt.k[ss] = k2[ss];
;   }
.Lasel_noscale:
	v_cvt_pk_bf16_f32 v224, v32, v33
	v_cvt_pk_bf16_f32 v225, v34, v35
	v_cvt_pk_bf16_f32 v226, v36, v37
	v_cvt_pk_bf16_f32 v227, v38, v39
	v_cvt_pk_bf16_f32 v228, v40, v41
	v_cvt_pk_bf16_f32 v229, v42, v43
	v_cvt_pk_bf16_f32 v230, v44, v45
	v_cvt_pk_bf16_f32 v231, v46, v47
	v_cvt_pk_bf16_f32 v232, v48, v49
	v_cvt_pk_bf16_f32 v233, v50, v51
	v_cvt_pk_bf16_f32 v234, v52, v53
	v_cvt_pk_bf16_f32 v235, v54, v55
	v_cvt_pk_bf16_f32 v236, v56, v57
	v_cvt_pk_bf16_f32 v237, v58, v59
	v_cvt_pk_bf16_f32 v238, v60, v61
	v_cvt_pk_bf16_f32 v239, v62, v63
	s_waitcnt lgkmcnt(0)
	s_nop 1
	v_mfma_f32_32x32x16_bf16 v[0:15], v[64:67], v[224:227], v[0:15]
	v_mfma_f32_32x32x16_bf16 v[16:31], v[68:71], v[224:227], v[16:31]
	v_mfma_f32_32x32x16_bf16 v[0:15], v[72:75], v[228:231], v[0:15]
	v_mfma_f32_32x32x16_bf16 v[16:31], v[76:79], v[228:231], v[16:31]
	v_mfma_f32_32x32x16_bf16 v[0:15], v[172:175], v[232:235], v[0:15]
	v_mfma_f32_32x32x16_bf16 v[16:31], v[176:179], v[232:235], v[16:31]
	v_mfma_f32_32x32x16_bf16 v[0:15], v[180:183], v[236:239], v[0:15]
	v_mfma_f32_32x32x16_bf16 v[16:31], v[184:187], v[236:239], v[16:31]
.Lasel_skip:
	s_add_u32 s100, s100, 0x4000
	s_cmp_eq_u32 s100, 0x1c000
	s_cselect_b32 s100, 0x10000, s100
	s_add_u32 s56, s56, 2
	s_cmp_le_u32 s56, s59
	s_cbranch_scc1 .Lasel_loop
	s_nop 15
	s_waitcnt vmcnt(0)
	s_mov_b64 s[58:59], 0
	s_branch .LBB0_701
